# gla pass 2 branch outputs written with non-temporal stores
# speedup vs baseline: 1.0041x; 1.0014x over previous
; #define LAS __attribute__((address_space(3)))
; __device__ __forceinline__ unsigned cvt_pk_bf16_mfma(float lo, float hi) { const f32x2 v = {lo, hi}; return __builtin_bit_cast(unsigned, __builtin_convertvector(v, bf16v2_t)); }
; template <bool OUT>
; __device__ __forceinline__ void gla_chunks(const Params& p, int l, const bf16_t* proj, LAS unsigned char* lds, int seg, int h, int dir, f32x4 (&Sacc)[4], float* outbuf, float& alog) {
;     ...
;         bf16x8 bv[2];
; #pragma unroll
;         for (int ks = 0; ks < 2; ++ks) bv[ks] = *(const LAS bf16x8*)(VT + (16 * wv + fr) * GP + 32 * ks + 8 * g);
;         if (OUT) {
;             bf16x8 bs[2];
; #pragma unroll
;             for (int m = 0; m < 2; ++m) { u32x4 sw; sw.x = cvt_pk_bf16_mfma(Sacc[2 * m][0], Sacc[2 * m][1]); sw.y = cvt_pk_bf16_mfma(Sacc[2 * m][2], Sacc[2 * m][3]); sw.z = cvt_pk_bf16_mfma(Sacc[2 * m + 1][0], Sacc[2 * m + 1][1]); sw.w = cvt_pk_bf16_mfma(Sacc[2 * m + 1][2], Sacc[2 * m + 1][3]); bs[m] = __builtin_bit_cast(bf16x8, sw); }
; #pragma unroll
;             for (int it = 0; it < 4; ++it) { f32x4 o = {0.f, 0.f, 0.f, 0.f};
; #pragma unroll
;                 for (int ks = 0; ks < 2; ++ks) { const bf16x8 pf = *(const LAS bf16x8*)(PP + (it * 16 + fr) * GP + 32 * ks + 8 * g); o = __builtin_amdgcn_mfma_f32_16x16x32_bf16(pf, bv[ks], o, 0, 0, 0); }
; #pragma unroll
;                 for (int m = 0; m < 2; ++m) { const LAS bf16_t* qp = QT + (it * 16 + fr) * GP + 32 * m + 4 * g; const u32x2 lo = *(const LAS u32x2*)qp, hi = *(const LAS u32x2*)(qp + 16);
;                     u32x4 qw; qw.x = lo.x; qw.y = lo.y; qw.z = hi.x; qw.w = hi.y; o = __builtin_amdgcn_mfma_f32_16x16x32_bf16(__builtin_bit_cast(bf16x8, qw), bs[m], o, 0, 0, 0); }
; #pragma unroll
;                 for (int r = 0; r < 4; ++r) { const int i = it * 16 + 4 * g + r, t = dir ? t0 + 63 - i : t0 + i; outbuf[(size_t)t * 512 + h * 128 + 16 * wv + fr] = o[r]; } }
;         }
; #pragma unroll
;         for (int dt = 0; dt < 4; ++dt) { const f32x4 eb = *(const LAS f32x4*)(EBL + dt * 16 + 4 * g); f32x4 a = Sacc[dt] * eb;
; #pragma unroll
;             for (int ks = 0; ks < 2; ++ks) { const bf16x8 kf = *(const LAS bf16x8*)(KH + (dt * 16 + fr) * GP + 32 * ks + 8 * g); a = __builtin_amdgcn_mfma_f32_16x16x32_bf16(kf, bv[ks], a, 0, 0, 0); }
;             Sacc[dt] = a; }
.Lp2b_rsdone:
	v_cvt_pk_bf16_f32 v16, v22, v16
	v_cvt_pk_bf16_f32 v17, v17, v18
	s_nop 0
	v_add_u32_e32 v18, v111, v118
	ds_write_b64 v18, v[16:17] offset:46080
	s_waitcnt lgkmcnt(0)
	s_barrier
	ds_read_b128 v[20:23], v135 offset:27648
	ds_read_b128 v[16:19], v135 offset:27712
	ds_read_b128 v[156:159], v136 offset:46080
	ds_read_b128 v[160:163], v136 offset:46144
	ds_read2_b64 v[190:193], v137 offset1:4
	ds_read2_b64 v[194:197], v137 offset0:8 offset1:12
	ds_read_b128 v[164:167], v136 offset:48384
	ds_read_b128 v[168:171], v136 offset:48448
	v_add_u32_e32 v40, 0x800, v137
	ds_read2_b64 v[198:201], v40 offset0:32 offset1:36
	ds_read2_b64 v[202:205], v40 offset0:40 offset1:44
	ds_read_b128 v[172:175], v136 offset:50688
	ds_read_b128 v[176:179], v136 offset:50752
	ds_read_b128 v[180:183], v136 offset:52992
	ds_read_b128 v[184:187], v136 offset:53056
	v_cvt_pk_bf16_f32 v28, v8, v9
	v_cvt_pk_bf16_f32 v29, v10, v11
	v_cvt_pk_bf16_f32 v30, v0, v1
	v_cvt_pk_bf16_f32 v31, v2, v3
	v_cvt_pk_bf16_f32 v24, v4, v5
	v_cvt_pk_bf16_f32 v25, v6, v7
	v_cvt_pk_bf16_f32 v26, v12, v13
	v_cvt_pk_bf16_f32 v27, v14, v15
	s_waitcnt lgkmcnt(11)
	v_mfma_f32_16x16x32_bf16 v[32:35], v[156:159], v[20:23], 0
	s_waitcnt lgkmcnt(10)
	v_mfma_f32_16x16x32_bf16 v[32:35], v[160:163], v[16:19], v[32:35]
	s_waitcnt lgkmcnt(9)
	v_mfma_f32_16x16x32_bf16 v[32:35], v[190:193], v[28:31], v[32:35]
	s_waitcnt lgkmcnt(8)
	v_mfma_f32_16x16x32_bf16 v[32:35], v[194:197], v[24:27], v[32:35]
	v_add_u32_e32 v40, 0x1000, v137
	ds_read2_b64 v[138:141], v40 offset0:64 offset1:68
	ds_read2_b64 v[142:145], v40 offset0:72 offset1:76
	v_add_u32_e32 v40, 0x1800, v137
	ds_read2_b64 v[146:149], v40 offset0:96 offset1:100
	ds_read2_b64 v[150:153], v40 offset0:104 offset1:108
	s_waitcnt lgkmcnt(11)
	v_mfma_f32_16x16x32_bf16 v[36:39], v[164:167], v[20:23], 0
	s_waitcnt lgkmcnt(10)
	v_mfma_f32_16x16x32_bf16 v[36:39], v[168:171], v[16:19], v[36:39]
	s_waitcnt lgkmcnt(9)
	v_mfma_f32_16x16x32_bf16 v[36:39], v[198:201], v[28:31], v[36:39]
	s_waitcnt lgkmcnt(8)
	v_mfma_f32_16x16x32_bf16 v[36:39], v[202:205], v[24:27], v[36:39]
	ds_write_b32 v41, v32
	ds_write_b32 v41, v33 offset:528
	ds_write_b32 v41, v34 offset:1056
	ds_write_b32 v41, v35 offset:1584
	s_waitcnt lgkmcnt(7)
	v_mfma_f32_16x16x32_bf16 v[32:35], v[172:175], v[20:23], 0
	s_waitcnt lgkmcnt(6)
	v_mfma_f32_16x16x32_bf16 v[32:35], v[176:179], v[16:19], v[32:35]
	s_waitcnt lgkmcnt(3)
	v_mfma_f32_16x16x32_bf16 v[32:35], v[138:141], v[28:31], v[32:35]
	s_waitcnt lgkmcnt(2)
	v_mfma_f32_16x16x32_bf16 v[32:35], v[142:145], v[24:27], v[32:35]
	ds_write_b32 v41, v36 offset:8448
	ds_write_b32 v41, v37 offset:8976
	ds_write_b32 v41, v38 offset:9504
	ds_write_b32 v41, v39 offset:10032
	ds_read_b128 v[156:159], v82 offset:55296
	ds_read_b128 v[160:163], v82 offset:55360
	ds_read_b128 v[164:167], v82 offset:55424
	ds_read_b128 v[168:171], v82 offset:55488
	ds_read_b128 v[190:193], v136 offset:18432
	ds_read_b128 v[194:197], v136 offset:18496
	ds_read_b128 v[198:201], v136 offset:20736
	ds_read_b128 v[202:205], v136 offset:20800
	v_mfma_f32_16x16x32_bf16 v[36:39], v[180:183], v[20:23], 0
	v_mfma_f32_16x16x32_bf16 v[36:39], v[184:187], v[16:19], v[36:39]
	s_waitcnt lgkmcnt(9)
	v_mfma_f32_16x16x32_bf16 v[36:39], v[146:149], v[28:31], v[36:39]
	s_waitcnt lgkmcnt(8)
	v_mfma_f32_16x16x32_bf16 v[36:39], v[150:153], v[24:27], v[36:39]
	ds_read_b128 v[172:175], v136 offset:23040
	ds_read_b128 v[176:179], v136 offset:23104
	ds_read_b128 v[180:183], v136 offset:25344
	ds_read_b128 v[184:187], v136 offset:25408
	ds_write_b32 v41, v32 offset:16896
	ds_write_b32 v41, v33 offset:17424
	ds_write_b32 v41, v34 offset:17952
	ds_write_b32 v41, v35 offset:18480
	s_waitcnt lgkmcnt(8)
	v_pk_mul_f32 v[8:9], v[8:9], v[156:157]
	v_pk_mul_f32 v[10:11], v[10:11], v[158:159]
	v_pk_mul_f32 v[0:1], v[0:1], v[160:161]
	v_pk_mul_f32 v[2:3], v[2:3], v[162:163]
	v_pk_mul_f32 v[4:5], v[4:5], v[164:165]
	v_pk_mul_f32 v[6:7], v[6:7], v[166:167]
	v_pk_mul_f32 v[12:13], v[12:13], v[168:169]
	v_pk_mul_f32 v[14:15], v[14:15], v[170:171]
	ds_write_b32 v41, v36 offset:25344
	ds_write_b32 v41, v37 offset:25872
	ds_write_b32 v41, v38 offset:26400
	ds_write_b32 v41, v39 offset:26928
	s_waitcnt lgkmcnt(7)
	v_mfma_f32_16x16x32_bf16 v[8:11], v[190:193], v[20:23], v[8:11]
	s_waitcnt lgkmcnt(6)
	v_mfma_f32_16x16x32_bf16 v[8:11], v[194:197], v[16:19], v[8:11]
	s_waitcnt lgkmcnt(5)
	v_mfma_f32_16x16x32_bf16 v[0:3], v[198:201], v[20:23], v[0:3]
	s_waitcnt lgkmcnt(4)
	v_mfma_f32_16x16x32_bf16 v[0:3], v[202:205], v[16:19], v[0:3]
	s_waitcnt lgkmcnt(3)
	v_mfma_f32_16x16x32_bf16 v[4:7], v[172:175], v[20:23], v[4:7]
	s_waitcnt lgkmcnt(2)
	v_mfma_f32_16x16x32_bf16 v[4:7], v[176:179], v[16:19], v[4:7]
	s_waitcnt lgkmcnt(1)
	v_mfma_f32_16x16x32_bf16 v[12:15], v[180:183], v[20:23], v[12:15]
	s_waitcnt lgkmcnt(0)
	v_mfma_f32_16x16x32_bf16 v[12:15], v[184:187], v[16:19], v[12:15]
	s_add_i32 s51, s51, 1
	s_add_i32 s64, s64, -1
	s_cmp_lg_u32 s51, 4
	s_waitcnt lgkmcnt(0)
	s_barrier
; __device__ void gla_pass2(const Params& p, int l, const bf16_t* proj, bf16_t* ycat, LAS unsigned char* lds) {
;     ...
;         const f32x2 gg = *(const f32x2*)(p.gng + l * 512 + h * 128 + lane * 2);
;         for (int j0 = 0; j0 < 32; j0 += 8) {
;             f32x2 of[8], ob[8]; unsigned rw[8];
; #pragma unroll
;             for (int j = 0; j < 8; ++j) { const int t = seg * SEGLEN + wv * 32 + j0 + j; const size_t oo = (size_t)t * 512 + h * 128 + lane * 2;
;                 of[j] = *(const f32x2*)(OF + oo); ob[j] = *(const f32x2*)(OB + oo); rw[j] = *(const unsigned*)(proj + (size_t)t * NP + GR + h * 128 + lane * 2); }
; #pragma unroll
;             for (int j = 0; j < 8; ++j) { const int t = seg * SEGLEN + wv * 32 + j0 + j;
;                 const float o0 = of[j][0] + ob[j][0], o1 = of[j][1] + ob[j][1];
;                 const float ss = wave_sum(o0 * o0 + o1 * o1);
	v_and_b32_e32 v166, 63, v83
	s_lshl_b32 s40, s66, 2
	v_lshlrev_b32_e32 v167, 2, v166
	v_add_u32_e32 v167, s40, v167
	v_lshl_add_u32 v168, v90, 13, v167
	v_mul_u32_u24_e32 v169, 0x1c000, v90
	v_add_u32_e32 v167, v169, v167
	v_lshlrev_b32_e32 v169, 3, v90
	v_sub_u32_e32 v170, 56, v169
	v_mul_u32_u24_e32 v170, 0x210, v170
	v_lshl_add_u32 v170, v166, 3, v170
	v_add_u32_e32 v170, 0xe400, v170
	v_mul_u32_u24_e32 v171, 0x210, v169
	v_lshl_add_u32 v171, v166, 3, v171
	v_add_u32_e32 v171, 0x16800, v171
	v_readlane_b32 s56, v255, 55
	v_readlane_b32 s57, v255, 56
	s_add_u32 s56, s56, s67
	s_addc_u32 s57, s57, 0
	v_lshlrev_b32_e32 v172, 3, v166
	s_nop 2
	global_load_dwordx2 v[156:157], v172, s[56:57]
	s_mul_i32 s40, s52, 0x3800
	s_add_u32 s40, s40, 0x20604200
	s_add_u32 s40, s86, s40
	s_addc_u32 s41, s87, 0
	global_load_dword v32, v167, s[40:41]
	s_add_u32 s40, s40, 0x3800
	s_addc_u32 s41, s41, 0
	global_load_dword v33, v167, s[40:41]
	s_add_u32 s40, s40, 0x3800
	s_addc_u32 s41, s41, 0
	global_load_dword v34, v167, s[40:41]
	s_add_u32 s40, s40, 0x3800
	s_addc_u32 s41, s41, 0
	global_load_dword v35, v167, s[40:41]
	s_add_u32 s40, s40, 0x3800
	s_addc_u32 s41, s41, 0
	global_load_dword v36, v167, s[40:41]
	s_add_u32 s40, s40, 0x3800
	s_addc_u32 s41, s41, 0
	global_load_dword v37, v167, s[40:41]
	s_add_u32 s40, s40, 0x3800
	s_addc_u32 s41, s41, 0
	global_load_dword v38, v167, s[40:41]
	s_add_u32 s40, s40, 0x3800
	s_addc_u32 s41, s41, 0
	global_load_dword v39, v167, s[40:41]
	ds_read_b64 v[138:139], v170 offset:3696
	ds_read_b64 v[140:141], v170 offset:3168
	ds_read_b64 v[142:143], v170 offset:2640
	ds_read_b64 v[144:145], v170 offset:2112
	ds_read_b64 v[146:147], v170 offset:1584
	ds_read_b64 v[148:149], v170 offset:1056
	ds_read_b64 v[150:151], v170 offset:528
	ds_read_b64 v[152:153], v170 offset:0
	ds_read_b64 v[16:17], v171
	ds_read_b64 v[18:19], v171 offset:528
	ds_read_b64 v[20:21], v171 offset:1056
	ds_read_b64 v[22:23], v171 offset:1584
	ds_read_b64 v[24:25], v171 offset:2112
	ds_read_b64 v[26:27], v171 offset:2640
	ds_read_b64 v[28:29], v171 offset:3168
	ds_read_b64 v[30:31], v171 offset:3696
	s_lshl_b32 s54, s52, 10
	s_add_u32 s54, s54, 0x30601000
	s_add_u32 s54, s86, s54
	s_addc_u32 s55, s87, 0
	s_add_u32 s56, s54, 0x1000
	s_addc_u32 s57, s55, 0
	s_waitcnt lgkmcnt(0)
	v_add_f32_e32 v16, v16, v138
	v_add_f32_e32 v17, v17, v139
	v_mul_f32_e32 v138, v16, v16
	v_mul_f32_e32 v139, v17, v17
	v_add_f32_e32 v138, v138, v139
	v_add_f32_e32 v18, v18, v140
	v_add_f32_e32 v19, v19, v141
	v_mul_f32_e32 v140, v18, v18
	v_mul_f32_e32 v141, v19, v19
	v_add_f32_e32 v140, v140, v141
	v_add_f32_e32 v20, v20, v142
	v_add_f32_e32 v21, v21, v143
	v_mul_f32_e32 v142, v20, v20
	v_mul_f32_e32 v143, v21, v21
	v_add_f32_e32 v142, v142, v143
	v_add_f32_e32 v22, v22, v144
	v_add_f32_e32 v23, v23, v145
	v_mul_f32_e32 v144, v22, v22
	v_mul_f32_e32 v145, v23, v23
	v_add_f32_e32 v144, v144, v145
	v_add_f32_e32 v24, v24, v146
	v_add_f32_e32 v25, v25, v147
	v_mul_f32_e32 v146, v24, v24
	v_mul_f32_e32 v147, v25, v25
	v_add_f32_e32 v146, v146, v147
	v_add_f32_e32 v26, v26, v148
	v_add_f32_e32 v27, v27, v149
	v_mul_f32_e32 v148, v26, v26
	v_mul_f32_e32 v149, v27, v27
	v_add_f32_e32 v148, v148, v149
	v_add_f32_e32 v28, v28, v150
	v_add_f32_e32 v29, v29, v151
	v_mul_f32_e32 v150, v28, v28
	v_mul_f32_e32 v151, v29, v29
	v_add_f32_e32 v150, v150, v151
	v_add_f32_e32 v30, v30, v152
	v_add_f32_e32 v31, v31, v153
	v_mul_f32_e32 v152, v30, v30
	v_mul_f32_e32 v153, v31, v31
	v_add_f32_e32 v152, v152, v153
	v_mov_b32_e32 v139, v138
	v_mov_b32_e32 v141, v140
	v_mov_b32_e32 v143, v142
	v_mov_b32_e32 v145, v144
	v_mov_b32_e32 v147, v146
	v_mov_b32_e32 v149, v148
	v_mov_b32_e32 v151, v150
	v_mov_b32_e32 v153, v152
	v_permlane32_swap_b32_e32 v139, v138
	v_permlane32_swap_b32_e32 v141, v140
	v_permlane32_swap_b32_e32 v143, v142
	v_permlane32_swap_b32_e32 v145, v144
	v_permlane32_swap_b32_e32 v147, v146
	v_permlane32_swap_b32_e32 v149, v148
	v_permlane32_swap_b32_e32 v151, v150
	v_permlane32_swap_b32_e32 v153, v152
	v_add_f32_e32 v138, v138, v139
	v_add_f32_e32 v140, v140, v141
	v_add_f32_e32 v142, v142, v143
	v_add_f32_e32 v144, v144, v145
	v_add_f32_e32 v146, v146, v147
	v_add_f32_e32 v148, v148, v149
	v_add_f32_e32 v150, v150, v151
	v_add_f32_e32 v152, v152, v153
	v_mov_b32_e32 v139, v138
	v_mov_b32_e32 v141, v140
	v_mov_b32_e32 v143, v142
	v_mov_b32_e32 v145, v144
	v_mov_b32_e32 v147, v146
	v_mov_b32_e32 v149, v148
	v_mov_b32_e32 v151, v150
	v_mov_b32_e32 v153, v152
	v_permlane16_swap_b32_e32 v139, v138
	v_permlane16_swap_b32_e32 v141, v140
	v_permlane16_swap_b32_e32 v143, v142
	v_permlane16_swap_b32_e32 v145, v144
	v_permlane16_swap_b32_e32 v147, v146
	v_permlane16_swap_b32_e32 v149, v148
	v_permlane16_swap_b32_e32 v151, v150
	v_permlane16_swap_b32_e32 v153, v152
	v_add_f32_e32 v138, v138, v139
	v_add_f32_e32 v140, v140, v141
	v_add_f32_e32 v142, v142, v143
	v_add_f32_e32 v144, v144, v145
	v_add_f32_e32 v146, v146, v147
	v_add_f32_e32 v148, v148, v149
	v_add_f32_e32 v150, v150, v151
	v_add_f32_e32 v152, v152, v153
	v_add_f32_dpp v138, v138, v138 row_ror:8 row_mask:0xf bank_mask:0xf
	v_add_f32_dpp v140, v140, v140 row_ror:8 row_mask:0xf bank_mask:0xf
	v_add_f32_dpp v142, v142, v142 row_ror:8 row_mask:0xf bank_mask:0xf
	v_add_f32_dpp v144, v144, v144 row_ror:8 row_mask:0xf bank_mask:0xf
	v_add_f32_dpp v146, v146, v146 row_ror:8 row_mask:0xf bank_mask:0xf
	v_add_f32_dpp v148, v148, v148 row_ror:8 row_mask:0xf bank_mask:0xf
	v_add_f32_dpp v150, v150, v150 row_ror:8 row_mask:0xf bank_mask:0xf
	v_add_f32_dpp v152, v152, v152 row_ror:8 row_mask:0xf bank_mask:0xf
; __device__ __forceinline__ unsigned cvt_pk_bf16(float lo, float hi) { unsigned r; asm("v_cvt_pk_bf16_f32 %0, %1, %2" : "=v"(r) : "v"(lo), "v"(hi)); return r; }
; __device__ __forceinline__ float bf_lo(unsigned w) { return __uint_as_float(w << 16); }
; __device__ __forceinline__ float bf_hi(unsigned w) { return __uint_as_float(w & 0xffff0000u); }
; __device__ void gla_pass2(const Params& p, int l, const bf16_t* proj, bf16_t* ycat, LAS unsigned char* lds) {
;     ...
;             for (int j = 0; j < 8; ++j) { const int t = seg * SEGLEN + wv * 32 + j0 + j;
;                 const float o0 = of[j][0] + ob[j][0], o1 = of[j][1] + ob[j][1];
;                 const float ss = wave_sum(o0 * o0 + o1 * o1);
;                 const float rs = rsqrtf(ss * (1.0f / 128.0f) + 1e-6f);
;                 const float r0 = bf_lo(rw[j]), r1 = bf_hi(rw[j]);
;                 const float y0 = o0 * rs * gg[0] * (r0 / (1.0f + __expf(-r0))), y1 = o1 * rs * gg[1] * (r1 / (1.0f + __expf(-r1)));
;                 *(unsigned*)(ycat + (size_t)2 * SEQ * 512 + (size_t)t * 512 + h * 128 + lane * 2) = cvt_pk_bf16(y0, y1); } }
	v_add_f32_dpp v138, v138, v138 row_ror:4 row_mask:0xf bank_mask:0xf
	v_add_f32_dpp v140, v140, v140 row_ror:4 row_mask:0xf bank_mask:0xf
	v_add_f32_dpp v142, v142, v142 row_ror:4 row_mask:0xf bank_mask:0xf
	v_add_f32_dpp v144, v144, v144 row_ror:4 row_mask:0xf bank_mask:0xf
	v_add_f32_dpp v146, v146, v146 row_ror:4 row_mask:0xf bank_mask:0xf
	v_add_f32_dpp v148, v148, v148 row_ror:4 row_mask:0xf bank_mask:0xf
	v_add_f32_dpp v150, v150, v150 row_ror:4 row_mask:0xf bank_mask:0xf
	v_add_f32_dpp v152, v152, v152 row_ror:4 row_mask:0xf bank_mask:0xf
	v_add_f32_dpp v138, v138, v138 quad_perm:[2,3,0,1] row_mask:0xf bank_mask:0xf
	v_add_f32_dpp v140, v140, v140 quad_perm:[2,3,0,1] row_mask:0xf bank_mask:0xf
	v_add_f32_dpp v142, v142, v142 quad_perm:[2,3,0,1] row_mask:0xf bank_mask:0xf
	v_add_f32_dpp v144, v144, v144 quad_perm:[2,3,0,1] row_mask:0xf bank_mask:0xf
	v_add_f32_dpp v146, v146, v146 quad_perm:[2,3,0,1] row_mask:0xf bank_mask:0xf
	v_add_f32_dpp v148, v148, v148 quad_perm:[2,3,0,1] row_mask:0xf bank_mask:0xf
	v_add_f32_dpp v150, v150, v150 quad_perm:[2,3,0,1] row_mask:0xf bank_mask:0xf
	v_add_f32_dpp v152, v152, v152 quad_perm:[2,3,0,1] row_mask:0xf bank_mask:0xf
	v_add_f32_dpp v138, v138, v138 quad_perm:[1,0,3,2] row_mask:0xf bank_mask:0xf
	v_add_f32_dpp v140, v140, v140 quad_perm:[1,0,3,2] row_mask:0xf bank_mask:0xf
	v_add_f32_dpp v142, v142, v142 quad_perm:[1,0,3,2] row_mask:0xf bank_mask:0xf
	v_add_f32_dpp v144, v144, v144 quad_perm:[1,0,3,2] row_mask:0xf bank_mask:0xf
	v_add_f32_dpp v146, v146, v146 quad_perm:[1,0,3,2] row_mask:0xf bank_mask:0xf
	v_add_f32_dpp v148, v148, v148 quad_perm:[1,0,3,2] row_mask:0xf bank_mask:0xf
	v_add_f32_dpp v150, v150, v150 quad_perm:[1,0,3,2] row_mask:0xf bank_mask:0xf
	v_add_f32_dpp v152, v152, v152 quad_perm:[1,0,3,2] row_mask:0xf bank_mask:0xf
	s_waitcnt vmcnt(0)
	v_fmamk_f32 v138, v138, 0x3c000000, v212
	v_cmp_gt_f32_e32 vcc, s1, v138
	v_mul_f32_e32 v174, 0x4b800000, v138
	v_lshlrev_b32_e32 v175, 16, v32
	v_cndmask_b32_e32 v138, v138, v174, vcc
	v_rsq_f32_e32 v138, v138
	v_and_b32_e32 v176, 0xffff0000, v32
	v_mul_f32_e32 v174, 0x45800000, v138
	v_mul_f32_e32 v177, 0xbfb8aa3b, v175
	v_cndmask_b32_e32 v138, v138, v174, vcc
	v_exp_f32_e32 v177, v177
	v_mul_f32_e32 v178, 0xbfb8aa3b, v176
	v_exp_f32_e32 v178, v178
	v_mul_f32_e32 v16, v16, v138
	v_mul_f32_e32 v17, v17, v138
	v_add_f32_e32 v177, 1.0, v177
	v_add_f32_e32 v178, 1.0, v178
	v_mul_f32_e32 v16, v156, v16
	v_mul_f32_e32 v17, v157, v17
	v_div_scale_f32 v179, s[40:41], v177, v177, v175
	v_div_scale_f32 v180, s[40:41], v178, v178, v176
	v_rcp_f32_e32 v181, v179
	v_rcp_f32_e32 v182, v180
	v_fma_f32 v183, -v179, v181, 1.0
	v_fma_f32 v184, -v180, v182, 1.0
	v_fmac_f32_e32 v181, v183, v181
	v_fmac_f32_e32 v182, v184, v182
	v_div_scale_f32 v183, vcc, v175, v177, v175
	v_mul_f32_e32 v185, v183, v181
	v_fma_f32 v187, -v179, v185, v183
	v_fmac_f32_e32 v185, v187, v181
	v_fma_f32 v179, -v179, v185, v183
	v_div_fmas_f32 v179, v179, v181, v185
	v_div_fixup_f32 v175, v179, v177, v175
	v_div_scale_f32 v184, vcc, v176, v178, v176
	v_mul_f32_e32 v186, v184, v182
	v_fma_f32 v187, -v180, v186, v184
	v_fmac_f32_e32 v186, v187, v182
	v_fma_f32 v180, -v180, v186, v184
	v_div_fmas_f32 v180, v180, v182, v186
	v_div_fixup_f32 v176, v180, v178, v176
	v_mul_f32_e32 v16, v175, v16
	v_mul_f32_e32 v17, v176, v17
	v_cvt_pk_bf16_f32 v158, v16, v17
	global_store_dword v168, v158, s[54:55] nt
	v_fmamk_f32 v140, v140, 0x3c000000, v212
	v_cmp_gt_f32_e32 vcc, s1, v140
	v_mul_f32_e32 v174, 0x4b800000, v140
	v_lshlrev_b32_e32 v175, 16, v33
	v_cndmask_b32_e32 v140, v140, v174, vcc
	v_rsq_f32_e32 v140, v140
	v_and_b32_e32 v176, 0xffff0000, v33
	v_mul_f32_e32 v174, 0x45800000, v140
	v_mul_f32_e32 v177, 0xbfb8aa3b, v175
	v_cndmask_b32_e32 v140, v140, v174, vcc
	v_exp_f32_e32 v177, v177
	v_mul_f32_e32 v178, 0xbfb8aa3b, v176
	v_exp_f32_e32 v178, v178
	v_mul_f32_e32 v18, v18, v140
	v_mul_f32_e32 v19, v19, v140
	v_add_f32_e32 v177, 1.0, v177
	v_add_f32_e32 v178, 1.0, v178
	v_mul_f32_e32 v18, v156, v18
	v_mul_f32_e32 v19, v157, v19
	v_div_scale_f32 v179, s[40:41], v177, v177, v175
	v_div_scale_f32 v180, s[40:41], v178, v178, v176
	v_rcp_f32_e32 v181, v179
	v_rcp_f32_e32 v182, v180
	v_fma_f32 v183, -v179, v181, 1.0
	v_fma_f32 v184, -v180, v182, 1.0
	v_fmac_f32_e32 v181, v183, v181
	v_fmac_f32_e32 v182, v184, v182
	v_div_scale_f32 v183, vcc, v175, v177, v175
	v_mul_f32_e32 v185, v183, v181
	v_fma_f32 v187, -v179, v185, v183
	v_fmac_f32_e32 v185, v187, v181
	v_fma_f32 v179, -v179, v185, v183
	v_div_fmas_f32 v179, v179, v181, v185
	v_div_fixup_f32 v175, v179, v177, v175
	v_div_scale_f32 v184, vcc, v176, v178, v176
	v_mul_f32_e32 v186, v184, v182
	v_fma_f32 v187, -v180, v186, v184
	v_fmac_f32_e32 v186, v187, v182
	v_fma_f32 v180, -v180, v186, v184
	v_div_fmas_f32 v180, v180, v182, v186
	v_div_fixup_f32 v176, v180, v178, v176
	v_mul_f32_e32 v18, v175, v18
	v_mul_f32_e32 v19, v176, v19
	v_cvt_pk_bf16_f32 v159, v18, v19
	global_store_dword v168, v159, s[54:55] offset:1024 nt
	v_fmamk_f32 v142, v142, 0x3c000000, v212
	v_cmp_gt_f32_e32 vcc, s1, v142
	v_mul_f32_e32 v174, 0x4b800000, v142
	v_lshlrev_b32_e32 v175, 16, v34
	v_cndmask_b32_e32 v142, v142, v174, vcc
	v_rsq_f32_e32 v142, v142
	v_and_b32_e32 v176, 0xffff0000, v34
	v_mul_f32_e32 v174, 0x45800000, v142
	v_mul_f32_e32 v177, 0xbfb8aa3b, v175
	v_cndmask_b32_e32 v142, v142, v174, vcc
	v_exp_f32_e32 v177, v177
	v_mul_f32_e32 v178, 0xbfb8aa3b, v176
	v_exp_f32_e32 v178, v178
	v_mul_f32_e32 v20, v20, v142
	v_mul_f32_e32 v21, v21, v142
	v_add_f32_e32 v177, 1.0, v177
	v_add_f32_e32 v178, 1.0, v178
	v_mul_f32_e32 v20, v156, v20
	v_mul_f32_e32 v21, v157, v21
; __device__ __forceinline__ unsigned cvt_pk_bf16(float lo, float hi) { unsigned r; asm("v_cvt_pk_bf16_f32 %0, %1, %2" : "=v"(r) : "v"(lo), "v"(hi)); return r; }
; __device__ __forceinline__ float bf_lo(unsigned w) { return __uint_as_float(w << 16); }
; __device__ __forceinline__ float bf_hi(unsigned w) { return __uint_as_float(w & 0xffff0000u); }
; __device__ void gla_pass2(const Params& p, int l, const bf16_t* proj, bf16_t* ycat, LAS unsigned char* lds) {
;     ...
;             for (int j = 0; j < 8; ++j) { const int t = seg * SEGLEN + wv * 32 + j0 + j;
;                 const float o0 = of[j][0] + ob[j][0], o1 = of[j][1] + ob[j][1];
;                 const float ss = wave_sum(o0 * o0 + o1 * o1);
;                 const float rs = rsqrtf(ss * (1.0f / 128.0f) + 1e-6f);
;                 const float r0 = bf_lo(rw[j]), r1 = bf_hi(rw[j]);
;                 const float y0 = o0 * rs * gg[0] * (r0 / (1.0f + __expf(-r0))), y1 = o1 * rs * gg[1] * (r1 / (1.0f + __expf(-r1)));
;                 *(unsigned*)(ycat + (size_t)2 * SEQ * 512 + (size_t)t * 512 + h * 128 + lane * 2) = cvt_pk_bf16(y0, y1); } }
	v_div_scale_f32 v179, s[40:41], v177, v177, v175
	v_div_scale_f32 v180, s[40:41], v178, v178, v176
	v_rcp_f32_e32 v181, v179
	v_rcp_f32_e32 v182, v180
	v_fma_f32 v183, -v179, v181, 1.0
	v_fma_f32 v184, -v180, v182, 1.0
	v_fmac_f32_e32 v181, v183, v181
	v_fmac_f32_e32 v182, v184, v182
	v_div_scale_f32 v183, vcc, v175, v177, v175
	v_mul_f32_e32 v185, v183, v181
	v_fma_f32 v187, -v179, v185, v183
	v_fmac_f32_e32 v185, v187, v181
	v_fma_f32 v179, -v179, v185, v183
	v_div_fmas_f32 v179, v179, v181, v185
	v_div_fixup_f32 v175, v179, v177, v175
	v_div_scale_f32 v184, vcc, v176, v178, v176
	v_mul_f32_e32 v186, v184, v182
	v_fma_f32 v187, -v180, v186, v184
	v_fmac_f32_e32 v186, v187, v182
	v_fma_f32 v180, -v180, v186, v184
	v_div_fmas_f32 v180, v180, v182, v186
	v_div_fixup_f32 v176, v180, v178, v176
	v_mul_f32_e32 v20, v175, v20
	v_mul_f32_e32 v21, v176, v21
	v_cvt_pk_bf16_f32 v160, v20, v21
	global_store_dword v168, v160, s[54:55] offset:2048 nt
	v_fmamk_f32 v144, v144, 0x3c000000, v212
	v_cmp_gt_f32_e32 vcc, s1, v144
	v_mul_f32_e32 v174, 0x4b800000, v144
	v_lshlrev_b32_e32 v175, 16, v35
	v_cndmask_b32_e32 v144, v144, v174, vcc
	v_rsq_f32_e32 v144, v144
	v_and_b32_e32 v176, 0xffff0000, v35
	v_mul_f32_e32 v174, 0x45800000, v144
	v_mul_f32_e32 v177, 0xbfb8aa3b, v175
	v_cndmask_b32_e32 v144, v144, v174, vcc
	v_exp_f32_e32 v177, v177
	v_mul_f32_e32 v178, 0xbfb8aa3b, v176
	v_exp_f32_e32 v178, v178
	v_mul_f32_e32 v22, v22, v144
	v_mul_f32_e32 v23, v23, v144
	v_add_f32_e32 v177, 1.0, v177
	v_add_f32_e32 v178, 1.0, v178
	v_mul_f32_e32 v22, v156, v22
	v_mul_f32_e32 v23, v157, v23
	v_div_scale_f32 v179, s[40:41], v177, v177, v175
	v_div_scale_f32 v180, s[40:41], v178, v178, v176
	v_rcp_f32_e32 v181, v179
	v_rcp_f32_e32 v182, v180
	v_fma_f32 v183, -v179, v181, 1.0
	v_fma_f32 v184, -v180, v182, 1.0
	v_fmac_f32_e32 v181, v183, v181
	v_fmac_f32_e32 v182, v184, v182
	v_div_scale_f32 v183, vcc, v175, v177, v175
	v_mul_f32_e32 v185, v183, v181
	v_fma_f32 v187, -v179, v185, v183
	v_fmac_f32_e32 v185, v187, v181
	v_fma_f32 v179, -v179, v185, v183
	v_div_fmas_f32 v179, v179, v181, v185
	v_div_fixup_f32 v175, v179, v177, v175
	v_div_scale_f32 v184, vcc, v176, v178, v176
	v_mul_f32_e32 v186, v184, v182
	v_fma_f32 v187, -v180, v186, v184
	v_fmac_f32_e32 v186, v187, v182
	v_fma_f32 v180, -v180, v186, v184
	v_div_fmas_f32 v180, v180, v182, v186
	v_div_fixup_f32 v176, v180, v178, v176
	v_mul_f32_e32 v22, v175, v22
	v_mul_f32_e32 v23, v176, v23
	v_cvt_pk_bf16_f32 v161, v22, v23
	global_store_dword v168, v161, s[54:55] offset:3072 nt
	v_fmamk_f32 v146, v146, 0x3c000000, v212
	v_cmp_gt_f32_e32 vcc, s1, v146
	v_mul_f32_e32 v174, 0x4b800000, v146
	v_lshlrev_b32_e32 v175, 16, v36
	v_cndmask_b32_e32 v146, v146, v174, vcc
	v_rsq_f32_e32 v146, v146
	v_and_b32_e32 v176, 0xffff0000, v36
	v_mul_f32_e32 v174, 0x45800000, v146
	v_mul_f32_e32 v177, 0xbfb8aa3b, v175
	v_cndmask_b32_e32 v146, v146, v174, vcc
	v_exp_f32_e32 v177, v177
	v_mul_f32_e32 v178, 0xbfb8aa3b, v176
	v_exp_f32_e32 v178, v178
	v_mul_f32_e32 v24, v24, v146
	v_mul_f32_e32 v25, v25, v146
	v_add_f32_e32 v177, 1.0, v177
	v_add_f32_e32 v178, 1.0, v178
	v_mul_f32_e32 v24, v156, v24
	v_mul_f32_e32 v25, v157, v25
	v_div_scale_f32 v179, s[40:41], v177, v177, v175
	v_div_scale_f32 v180, s[40:41], v178, v178, v176
	v_rcp_f32_e32 v181, v179
	v_rcp_f32_e32 v182, v180
	v_fma_f32 v183, -v179, v181, 1.0
	v_fma_f32 v184, -v180, v182, 1.0
	v_fmac_f32_e32 v181, v183, v181
	v_fmac_f32_e32 v182, v184, v182
	v_div_scale_f32 v183, vcc, v175, v177, v175
	v_mul_f32_e32 v185, v183, v181
	v_fma_f32 v187, -v179, v185, v183
	v_fmac_f32_e32 v185, v187, v181
	v_fma_f32 v179, -v179, v185, v183
	v_div_fmas_f32 v179, v179, v181, v185
	v_div_fixup_f32 v175, v179, v177, v175
	v_div_scale_f32 v184, vcc, v176, v178, v176
	v_mul_f32_e32 v186, v184, v182
	v_fma_f32 v187, -v180, v186, v184
	v_fmac_f32_e32 v186, v187, v182
	v_fma_f32 v180, -v180, v186, v184
	v_div_fmas_f32 v180, v180, v182, v186
	v_div_fixup_f32 v176, v180, v178, v176
	v_mul_f32_e32 v24, v175, v24
	v_mul_f32_e32 v25, v176, v25
	v_cvt_pk_bf16_f32 v162, v24, v25
	global_store_dword v168, v162, s[56:57] nt
	v_fmamk_f32 v148, v148, 0x3c000000, v212
	v_cmp_gt_f32_e32 vcc, s1, v148
	v_mul_f32_e32 v174, 0x4b800000, v148
	v_lshlrev_b32_e32 v175, 16, v37
	v_cndmask_b32_e32 v148, v148, v174, vcc
	v_rsq_f32_e32 v148, v148
	v_and_b32_e32 v176, 0xffff0000, v37
	v_mul_f32_e32 v174, 0x45800000, v148
	v_mul_f32_e32 v177, 0xbfb8aa3b, v175
	v_cndmask_b32_e32 v148, v148, v174, vcc
; __device__ __forceinline__ unsigned cvt_pk_bf16(float lo, float hi) { unsigned r; asm("v_cvt_pk_bf16_f32 %0, %1, %2" : "=v"(r) : "v"(lo), "v"(hi)); return r; }
; __device__ __forceinline__ float bf_lo(unsigned w) { return __uint_as_float(w << 16); }
; __device__ __forceinline__ float bf_hi(unsigned w) { return __uint_as_float(w & 0xffff0000u); }
; __device__ void gla_pass2(const Params& p, int l, const bf16_t* proj, bf16_t* ycat, LAS unsigned char* lds) {
;     ...
;             for (int j = 0; j < 8; ++j) { const int t = seg * SEGLEN + wv * 32 + j0 + j;
;                 const float o0 = of[j][0] + ob[j][0], o1 = of[j][1] + ob[j][1];
;                 const float ss = wave_sum(o0 * o0 + o1 * o1);
;                 const float rs = rsqrtf(ss * (1.0f / 128.0f) + 1e-6f);
;                 const float r0 = bf_lo(rw[j]), r1 = bf_hi(rw[j]);
;                 const float y0 = o0 * rs * gg[0] * (r0 / (1.0f + __expf(-r0))), y1 = o1 * rs * gg[1] * (r1 / (1.0f + __expf(-r1)));
;                 *(unsigned*)(ycat + (size_t)2 * SEQ * 512 + (size_t)t * 512 + h * 128 + lane * 2) = cvt_pk_bf16(y0, y1); } }
	v_exp_f32_e32 v177, v177
	v_mul_f32_e32 v178, 0xbfb8aa3b, v176
	v_exp_f32_e32 v178, v178
	v_mul_f32_e32 v26, v26, v148
	v_mul_f32_e32 v27, v27, v148
	v_add_f32_e32 v177, 1.0, v177
	v_add_f32_e32 v178, 1.0, v178
	v_mul_f32_e32 v26, v156, v26
	v_mul_f32_e32 v27, v157, v27
	v_div_scale_f32 v179, s[40:41], v177, v177, v175
	v_div_scale_f32 v180, s[40:41], v178, v178, v176
	v_rcp_f32_e32 v181, v179
	v_rcp_f32_e32 v182, v180
	v_fma_f32 v183, -v179, v181, 1.0
	v_fma_f32 v184, -v180, v182, 1.0
	v_fmac_f32_e32 v181, v183, v181
	v_fmac_f32_e32 v182, v184, v182
	v_div_scale_f32 v183, vcc, v175, v177, v175
	v_mul_f32_e32 v185, v183, v181
	v_fma_f32 v187, -v179, v185, v183
	v_fmac_f32_e32 v185, v187, v181
	v_fma_f32 v179, -v179, v185, v183
	v_div_fmas_f32 v179, v179, v181, v185
	v_div_fixup_f32 v175, v179, v177, v175
	v_div_scale_f32 v184, vcc, v176, v178, v176
	v_mul_f32_e32 v186, v184, v182
	v_fma_f32 v187, -v180, v186, v184
	v_fmac_f32_e32 v186, v187, v182
	v_fma_f32 v180, -v180, v186, v184
	v_div_fmas_f32 v180, v180, v182, v186
	v_div_fixup_f32 v176, v180, v178, v176
	v_mul_f32_e32 v26, v175, v26
	v_mul_f32_e32 v27, v176, v27
	v_cvt_pk_bf16_f32 v163, v26, v27
	global_store_dword v168, v163, s[56:57] offset:1024 nt
	v_fmamk_f32 v150, v150, 0x3c000000, v212
	v_cmp_gt_f32_e32 vcc, s1, v150
	v_mul_f32_e32 v174, 0x4b800000, v150
	v_lshlrev_b32_e32 v175, 16, v38
	v_cndmask_b32_e32 v150, v150, v174, vcc
	v_rsq_f32_e32 v150, v150
	v_and_b32_e32 v176, 0xffff0000, v38
	v_mul_f32_e32 v174, 0x45800000, v150
	v_mul_f32_e32 v177, 0xbfb8aa3b, v175
	v_cndmask_b32_e32 v150, v150, v174, vcc
	v_exp_f32_e32 v177, v177
	v_mul_f32_e32 v178, 0xbfb8aa3b, v176
	v_exp_f32_e32 v178, v178
	v_mul_f32_e32 v28, v28, v150
	v_mul_f32_e32 v29, v29, v150
	v_add_f32_e32 v177, 1.0, v177
	v_add_f32_e32 v178, 1.0, v178
	v_mul_f32_e32 v28, v156, v28
	v_mul_f32_e32 v29, v157, v29
	v_div_scale_f32 v179, s[40:41], v177, v177, v175
	v_div_scale_f32 v180, s[40:41], v178, v178, v176
	v_rcp_f32_e32 v181, v179
	v_rcp_f32_e32 v182, v180
	v_fma_f32 v183, -v179, v181, 1.0
	v_fma_f32 v184, -v180, v182, 1.0
	v_fmac_f32_e32 v181, v183, v181
	v_fmac_f32_e32 v182, v184, v182
	v_div_scale_f32 v183, vcc, v175, v177, v175
	v_mul_f32_e32 v185, v183, v181
	v_fma_f32 v187, -v179, v185, v183
	v_fmac_f32_e32 v185, v187, v181
	v_fma_f32 v179, -v179, v185, v183
	v_div_fmas_f32 v179, v179, v181, v185
	v_div_fixup_f32 v175, v179, v177, v175
	v_div_scale_f32 v184, vcc, v176, v178, v176
	v_mul_f32_e32 v186, v184, v182
	v_fma_f32 v187, -v180, v186, v184
	v_fmac_f32_e32 v186, v187, v182
	v_fma_f32 v180, -v180, v186, v184
	v_div_fmas_f32 v180, v180, v182, v186
	v_div_fixup_f32 v176, v180, v178, v176
	v_mul_f32_e32 v28, v175, v28
	v_mul_f32_e32 v29, v176, v29
	v_cvt_pk_bf16_f32 v164, v28, v29
	global_store_dword v168, v164, s[56:57] offset:2048 nt
	v_fmamk_f32 v152, v152, 0x3c000000, v212
	v_cmp_gt_f32_e32 vcc, s1, v152
	v_mul_f32_e32 v174, 0x4b800000, v152
	v_lshlrev_b32_e32 v175, 16, v39
	v_cndmask_b32_e32 v152, v152, v174, vcc
	v_rsq_f32_e32 v152, v152
	v_and_b32_e32 v176, 0xffff0000, v39
	v_mul_f32_e32 v174, 0x45800000, v152
	v_mul_f32_e32 v177, 0xbfb8aa3b, v175
	v_cndmask_b32_e32 v152, v152, v174, vcc
	v_exp_f32_e32 v177, v177
	v_mul_f32_e32 v178, 0xbfb8aa3b, v176
	v_exp_f32_e32 v178, v178
	v_mul_f32_e32 v30, v30, v152
	v_mul_f32_e32 v31, v31, v152
	v_add_f32_e32 v177, 1.0, v177
	v_add_f32_e32 v178, 1.0, v178
	v_mul_f32_e32 v30, v156, v30
	v_mul_f32_e32 v31, v157, v31
	v_div_scale_f32 v179, s[40:41], v177, v177, v175
	v_div_scale_f32 v180, s[40:41], v178, v178, v176
	v_rcp_f32_e32 v181, v179
	v_rcp_f32_e32 v182, v180
	v_fma_f32 v183, -v179, v181, 1.0
	v_fma_f32 v184, -v180, v182, 1.0
	v_fmac_f32_e32 v181, v183, v181
	v_fmac_f32_e32 v182, v184, v182
	v_div_scale_f32 v183, vcc, v175, v177, v175
	v_mul_f32_e32 v185, v183, v181
	v_fma_f32 v187, -v179, v185, v183
	v_fmac_f32_e32 v185, v187, v181
	v_fma_f32 v179, -v179, v185, v183
	v_div_fmas_f32 v179, v179, v181, v185
	v_div_fixup_f32 v175, v179, v177, v175
	v_div_scale_f32 v184, vcc, v176, v178, v176
	v_mul_f32_e32 v186, v184, v182
	v_fma_f32 v187, -v180, v186, v184
	v_fmac_f32_e32 v186, v187, v182
	v_fma_f32 v180, -v180, v186, v184
	v_div_fmas_f32 v180, v180, v182, v186
	v_div_fixup_f32 v176, v180, v178, v176
	v_mul_f32_e32 v30, v175, v30
	v_mul_f32_e32 v31, v176, v31
	v_cvt_pk_bf16_f32 v165, v30, v31
	global_store_dword v168, v165, s[56:57] offset:3072 nt
	s_cmp_lg_u32 s51, 4
	s_cbranch_scc0 .LBB0_433
	s_branch .LBB0_436
